# strategy 7.4: one static s_setprio 1 for the younger wave half (waves 4-7) over the hd-64 attention unit, no per-block priority flips, on top of GEMM hand-off
# baseline (speedup 1.0000x reference)
.LBB0_924:
	v_readfirstlane_b32 s0, v0
	s_nop 3
	s_and_b32 s0, s0, 0x3ff
	s_lshr_b32 s0, s0, 8
	s_cmp_eq_u32 s0, 0
	s_cbranch_scc1 .Latt64_prio_done
	s_setprio 1

.LBB0_977:
	s_setprio 0
	v_mov_b32_e32 v16, v0
	s_cmp_lt_i32 s48, 0
	v_ashrrev_i32_e32 v17, 31, v16
	v_lshlrev_b64 v[70:71], 8, v[16:17]
	v_lshl_add_u64 v[70:71], s[40:41], 0, v[70:71]
	flat_load_dwordx4 v[130:133], v[70:71]
	flat_load_dwordx4 v[126:129], v[70:71] offset:16
	flat_load_dwordx4 v[122:125], v[70:71] offset:32
	flat_load_dwordx4 v[118:121], v[70:71] offset:48
	flat_load_dwordx4 v[114:117], v[70:71] offset:64
	flat_load_dwordx4 v[110:113], v[70:71] offset:80
	flat_load_dwordx4 v[106:109], v[70:71] offset:96
	flat_load_dwordx4 v[102:105], v[70:71] offset:112
	flat_load_dwordx4 v[98:101], v[70:71] offset:128
	flat_load_dwordx4 v[94:97], v[70:71] offset:144
	flat_load_dwordx4 v[90:93], v[70:71] offset:160
	flat_load_dwordx4 v[86:89], v[70:71] offset:176
	flat_load_dwordx4 v[82:85], v[70:71] offset:192
	flat_load_dwordx4 v[78:81], v[70:71] offset:208
	flat_load_dwordx4 v[74:77], v[70:71] offset:224
	s_nop 0
	flat_load_dwordx4 v[70:73], v[70:71] offset:240
	v_lshrrev_b32_e32 v3, 1, v16
	v_mov_b32_e32 v17, v2
	v_and_b32_e32 v16, 16, v3
	v_lshl_add_u64 v[16:17], s[8:9], 0, v[16:17]
	flat_load_dwordx4 v[146:149], v[16:17]
	flat_load_dwordx4 v[142:145], v[16:17] offset:32
	flat_load_dwordx4 v[138:141], v[16:17] offset:64
	flat_load_dwordx4 v[134:137], v[16:17] offset:96
	flat_load_dwordx4 v[162:165], v[16:17] offset:128
	flat_load_dwordx4 v[158:161], v[16:17] offset:160
	flat_load_dwordx4 v[154:157], v[16:17] offset:192
	flat_load_dwordx4 v[150:153], v[16:17] offset:224
	flat_load_dwordx4 v[178:181], v[16:17] offset:256
	flat_load_dwordx4 v[174:177], v[16:17] offset:288
	flat_load_dwordx4 v[170:173], v[16:17] offset:320
	flat_load_dwordx4 v[166:169], v[16:17] offset:352
	flat_load_dwordx4 v[194:197], v[16:17] offset:384
	flat_load_dwordx4 v[190:193], v[16:17] offset:416
	flat_load_dwordx4 v[186:189], v[16:17] offset:448
	flat_load_dwordx4 v[182:185], v[16:17] offset:480
	s_cselect_b64 s[18:19], -1, 0
	s_and_b64 s[0:1], s[4:5], s[36:37]
	s_or_b64 s[0:1], s[18:19], s[0:1]
	s_andn2_b64 vcc, exec, s[0:1]
	s_waitcnt lgkmcnt(0)
	s_barrier
	s_waitcnt vmcnt(0)
	v_pk_fma_f32 v[202:203], v[200:201], v[66:67], v[130:131] op_sel_hi:[0,1,1] neg_lo:[1,0,0] neg_hi:[1,0,0]
	v_mul_f32_e32 v3, v203, v203
	v_pk_fma_f32 v[132:133], v[200:201], v[68:69], v[132:133] op_sel_hi:[0,1,1] neg_lo:[1,0,0] neg_hi:[1,0,0]
	v_fmac_f32_e32 v3, v202, v202
	v_fmac_f32_e32 v3, v132, v132
	v_pk_fma_f32 v[130:131], v[200:201], v[12:13], v[126:127] op_sel_hi:[0,1,1] neg_lo:[1,0,0] neg_hi:[1,0,0]
	v_fmac_f32_e32 v3, v133, v133
	v_fmac_f32_e32 v3, v130, v130
	v_pk_fma_f32 v[128:129], v[200:201], v[14:15], v[128:129] op_sel_hi:[0,1,1] neg_lo:[1,0,0] neg_hi:[1,0,0]
	v_fmac_f32_e32 v3, v131, v131
	v_fmac_f32_e32 v3, v128, v128
	v_pk_fma_f32 v[126:127], v[200:201], v[8:9], v[122:123] op_sel_hi:[0,1,1] neg_lo:[1,0,0] neg_hi:[1,0,0]
	v_fmac_f32_e32 v3, v129, v129
	v_fmac_f32_e32 v3, v126, v126
	v_pk_fma_f32 v[124:125], v[200:201], v[10:11], v[124:125] op_sel_hi:[0,1,1] neg_lo:[1,0,0] neg_hi:[1,0,0]
	v_fmac_f32_e32 v3, v127, v127
	v_fmac_f32_e32 v3, v124, v124
	v_pk_fma_f32 v[122:123], v[200:201], v[4:5], v[118:119] op_sel_hi:[0,1,1] neg_lo:[1,0,0] neg_hi:[1,0,0]
	v_fmac_f32_e32 v3, v125, v125
	v_fmac_f32_e32 v3, v122, v122
	v_pk_fma_f32 v[120:121], v[200:201], v[6:7], v[120:121] op_sel_hi:[0,1,1] neg_lo:[1,0,0] neg_hi:[1,0,0]
	v_fmac_f32_e32 v3, v123, v123
	v_fmac_f32_e32 v3, v120, v120
	v_pk_fma_f32 v[118:119], v[200:201], v[50:51], v[114:115] op_sel_hi:[0,1,1] neg_lo:[1,0,0] neg_hi:[1,0,0]
	v_fmac_f32_e32 v3, v121, v121
	v_fmac_f32_e32 v3, v118, v118
	v_pk_fma_f32 v[116:117], v[200:201], v[52:53], v[116:117] op_sel_hi:[0,1,1] neg_lo:[1,0,0] neg_hi:[1,0,0]
	v_fmac_f32_e32 v3, v119, v119
	v_fmac_f32_e32 v3, v116, v116
	v_pk_fma_f32 v[114:115], v[200:201], v[54:55], v[110:111] op_sel_hi:[0,1,1] neg_lo:[1,0,0] neg_hi:[1,0,0]
	v_fmac_f32_e32 v3, v117, v117
	v_fmac_f32_e32 v3, v114, v114
	v_pk_fma_f32 v[110:111], v[200:201], v[56:57], v[112:113] op_sel_hi:[0,1,1] neg_lo:[1,0,0] neg_hi:[1,0,0]
	v_fmac_f32_e32 v3, v115, v115
	v_fmac_f32_e32 v3, v110, v110
	v_pk_fma_f32 v[68:69], v[200:201], v[58:59], v[106:107] op_sel_hi:[0,1,1] neg_lo:[1,0,0] neg_hi:[1,0,0]
	v_fmac_f32_e32 v3, v111, v111
	v_fmac_f32_e32 v3, v68, v68
	v_pk_fma_f32 v[66:67], v[200:201], v[60:61], v[108:109] op_sel_hi:[0,1,1] neg_lo:[1,0,0] neg_hi:[1,0,0]
	v_fmac_f32_e32 v3, v69, v69
	v_fmac_f32_e32 v3, v66, v66
	v_pk_fma_f32 v[60:61], v[200:201], v[62:63], v[102:103] op_sel_hi:[0,1,1] neg_lo:[1,0,0] neg_hi:[1,0,0]
	v_fmac_f32_e32 v3, v67, v67
	v_fmac_f32_e32 v3, v60, v60
	v_pk_fma_f32 v[58:59], v[200:201], v[64:65], v[104:105] op_sel_hi:[0,1,1] neg_lo:[1,0,0] neg_hi:[1,0,0]
	v_fmac_f32_e32 v3, v61, v61
	v_fmac_f32_e32 v3, v58, v58
	v_pk_fma_f32 v[56:57], v[200:201], v[34:35], v[98:99] op_sel_hi:[0,1,1] neg_lo:[1,0,0] neg_hi:[1,0,0]
	v_fmac_f32_e32 v3, v59, v59
	v_fmac_f32_e32 v3, v56, v56
	v_pk_fma_f32 v[54:55], v[200:201], v[36:37], v[100:101] op_sel_hi:[0,1,1] neg_lo:[1,0,0] neg_hi:[1,0,0]
	v_fmac_f32_e32 v3, v57, v57
	v_fmac_f32_e32 v3, v54, v54
	v_pk_fma_f32 v[52:53], v[200:201], v[38:39], v[94:95] op_sel_hi:[0,1,1] neg_lo:[1,0,0] neg_hi:[1,0,0]
	v_fmac_f32_e32 v3, v55, v55
	v_fmac_f32_e32 v3, v52, v52
	v_pk_fma_f32 v[50:51], v[200:201], v[40:41], v[96:97] op_sel_hi:[0,1,1] neg_lo:[1,0,0] neg_hi:[1,0,0]
	v_fmac_f32_e32 v3, v53, v53
	v_fmac_f32_e32 v3, v50, v50
	v_pk_fma_f32 v[40:41], v[200:201], v[42:43], v[90:91] op_sel_hi:[0,1,1] neg_lo:[1,0,0] neg_hi:[1,0,0]
	v_fmac_f32_e32 v3, v51, v51
	v_fmac_f32_e32 v3, v40, v40
	v_pk_fma_f32 v[38:39], v[200:201], v[44:45], v[92:93] op_sel_hi:[0,1,1] neg_lo:[1,0,0] neg_hi:[1,0,0]
	v_fmac_f32_e32 v3, v41, v41
	v_fmac_f32_e32 v3, v38, v38
	v_pk_fma_f32 v[36:37], v[200:201], v[46:47], v[86:87] op_sel_hi:[0,1,1] neg_lo:[1,0,0] neg_hi:[1,0,0]
	v_fmac_f32_e32 v3, v39, v39
	v_fmac_f32_e32 v3, v36, v36
	v_pk_fma_f32 v[34:35], v[200:201], v[48:49], v[88:89] op_sel_hi:[0,1,1] neg_lo:[1,0,0] neg_hi:[1,0,0]
	v_fmac_f32_e32 v3, v37, v37
	v_fmac_f32_e32 v3, v34, v34
	v_pk_fma_f32 v[18:19], v[200:201], v[18:19], v[82:83] op_sel_hi:[0,1,1] neg_lo:[1,0,0] neg_hi:[1,0,0]
	v_fmac_f32_e32 v3, v35, v35
	v_fmac_f32_e32 v3, v18, v18
	v_pk_fma_f32 v[16:17], v[200:201], v[20:21], v[84:85] op_sel_hi:[0,1,1] neg_lo:[1,0,0] neg_hi:[1,0,0]
	v_fmac_f32_e32 v3, v19, v19
	v_fmac_f32_e32 v3, v16, v16
	v_pk_fma_f32 v[14:15], v[200:201], v[22:23], v[78:79] op_sel_hi:[0,1,1] neg_lo:[1,0,0] neg_hi:[1,0,0]
	v_fmac_f32_e32 v3, v17, v17
	v_fmac_f32_e32 v3, v14, v14
	v_pk_fma_f32 v[12:13], v[200:201], v[24:25], v[80:81] op_sel_hi:[0,1,1] neg_lo:[1,0,0] neg_hi:[1,0,0]
	v_fmac_f32_e32 v3, v15, v15
	v_fmac_f32_e32 v3, v12, v12
	v_pk_fma_f32 v[10:11], v[200:201], v[26:27], v[74:75] op_sel_hi:[0,1,1] neg_lo:[1,0,0] neg_hi:[1,0,0]
	v_fmac_f32_e32 v3, v13, v13
	v_fmac_f32_e32 v3, v10, v10
	v_pk_fma_f32 v[8:9], v[200:201], v[28:29], v[76:77] op_sel_hi:[0,1,1] neg_lo:[1,0,0] neg_hi:[1,0,0]
	v_fmac_f32_e32 v3, v11, v11
	v_fmac_f32_e32 v3, v8, v8
	v_pk_fma_f32 v[6:7], v[200:201], v[30:31], v[70:71] op_sel_hi:[0,1,1] neg_lo:[1,0,0] neg_hi:[1,0,0]
	v_fmac_f32_e32 v3, v9, v9
	v_fmac_f32_e32 v3, v6, v6
	v_pk_fma_f32 v[4:5], v[200:201], v[32:33], v[72:73] op_sel_hi:[0,1,1] neg_lo:[1,0,0] neg_hi:[1,0,0]
	v_fmac_f32_e32 v3, v7, v7
	v_fmac_f32_e32 v3, v4, v4
	v_fmac_f32_e32 v3, v5, v5
	v_mov_b32_e32 v20, v3
	s_nop 1
	v_permlane32_swap_b32_e32 v3, v20
	s_cbranch_vccz .LBB0_911
	v_add_f32_e32 v3, v3, v20
	v_fmamk_f32 v3, v3, 0x3c000000, v1
	s_mov_b32 s0, 0xf800000
	v_mul_f32_e32 v20, 0x4f800000, v3
	v_cmp_gt_f32_e32 vcc, s0, v3
	s_nop 1
	v_cndmask_b32_e32 v3, v3, v20, vcc
	v_sqrt_f32_e32 v20, v3
	s_nop 0
	v_add_u32_e32 v21, -1, v20
	v_fma_f32 v23, -v21, v20, v3
	v_add_u32_e32 v22, 1, v20
	v_cmp_ge_f32_e64 s[4:5], 0, v23
	s_nop 1
	v_cndmask_b32_e64 v21, v20, v21, s[4:5]
	v_fma_f32 v20, -v22, v20, v3
	v_cmp_lt_f32_e64 s[4:5], 0, v20
	s_nop 1
	v_cndmask_b32_e64 v20, v21, v22, s[4:5]
	v_mul_f32_e32 v21, 0x37800000, v20
	v_cndmask_b32_e32 v20, v20, v21, vcc
	v_cmp_class_f32_e32 vcc, v3, v201
	s_nop 1
	v_cndmask_b32_e32 v3, v20, v3, vcc
	v_div_scale_f32 v20, s[0:1], v3, v3, s39
	v_rcp_f32_e32 v21, v20
	s_mov_b32 s0, 0x8000
	v_fma_f32 v22, -v20, v21, 1.0
	v_fmac_f32_e32 v21, v22, v21
	v_div_scale_f32 v22, vcc, s39, v3, s39
	v_mul_f32_e32 v23, v22, v21
	v_fma_f32 v24, -v20, v23, v22
	v_fmac_f32_e32 v23, v24, v21
	v_fma_f32 v20, -v20, v23, v22
	v_div_fmas_f32 v20, v20, v21, v23
	v_div_fixup_f32 v48, v20, v3, s39
	v_mov_b32_e32 v3, v0
	v_pk_mul_f32 v[94:95], v[148:149], v[48:49] op_sel_hi:[1,0]
	v_pk_mul_f32 v[96:97], v[146:147], v[48:49] op_sel_hi:[1,0]
	v_lshlrev_b32_e32 v108, 7, v3
	v_bfe_u32 v113, v3, 3, 3
	v_lshlrev_b32_e32 v112, 4, v3
	v_lshrrev_b32_e32 v3, 2, v3
	v_and_b32_e32 v109, 0xf80, v108
	v_lshlrev_b32_e32 v108, 12, v113
	v_and_b32_e32 v112, 0x70, v112
	v_lshlrev_b32_e32 v113, 7, v113
	v_and_b32_e32 v3, 8, v3
	v_pk_mul_f32 v[96:97], v[202:203], v[96:97]
	v_pk_mul_f32 v[94:95], v[132:133], v[94:95]
	v_pk_mul_f32 v[32:33], v[48:49], v[196:197] op_sel_hi:[0,1]
	v_pk_mul_f32 v[42:43], v[48:49], v[194:195] op_sel_hi:[0,1]
	v_pk_mul_f32 v[28:29], v[48:49], v[192:193] op_sel_hi:[0,1]
	v_pk_mul_f32 v[30:31], v[48:49], v[190:191] op_sel_hi:[0,1]
	v_pk_mul_f32 v[24:25], v[48:49], v[188:189] op_sel_hi:[0,1]
	v_pk_mul_f32 v[26:27], v[48:49], v[186:187] op_sel_hi:[0,1]
	v_pk_mul_f32 v[20:21], v[48:49], v[184:185] op_sel_hi:[0,1]
	v_pk_mul_f32 v[22:23], v[48:49], v[182:183] op_sel_hi:[0,1]
	v_pk_mul_f32 v[62:63], v[48:49], v[180:181] op_sel_hi:[0,1]
	v_pk_mul_f32 v[64:65], v[48:49], v[178:179] op_sel_hi:[0,1]
	v_pk_mul_f32 v[70:71], v[48:49], v[176:177] op_sel_hi:[0,1]
	v_pk_mul_f32 v[72:73], v[48:49], v[174:175] op_sel_hi:[0,1]
	v_pk_mul_f32 v[74:75], v[48:49], v[172:173] op_sel_hi:[0,1]
	v_pk_mul_f32 v[76:77], v[48:49], v[170:171] op_sel_hi:[0,1]
	v_pk_mul_f32 v[44:45], v[48:49], v[168:169] op_sel_hi:[0,1]
	v_pk_mul_f32 v[46:47], v[48:49], v[166:167] op_sel_hi:[0,1]
	v_pk_mul_f32 v[78:79], v[48:49], v[164:165] op_sel_hi:[0,1]
	v_pk_mul_f32 v[80:81], v[48:49], v[162:163] op_sel_hi:[0,1]
	v_pk_mul_f32 v[82:83], v[48:49], v[160:161] op_sel_hi:[0,1]
	v_pk_mul_f32 v[84:85], v[48:49], v[158:159] op_sel_hi:[0,1]
	v_pk_mul_f32 v[86:87], v[48:49], v[156:157] op_sel_hi:[0,1]
	v_pk_mul_f32 v[88:89], v[48:49], v[154:155] op_sel_hi:[0,1]
	v_pk_mul_f32 v[90:91], v[48:49], v[152:153] op_sel_hi:[0,1]
	v_pk_mul_f32 v[92:93], v[48:49], v[150:151] op_sel_hi:[0,1]
	v_pk_mul_f32 v[98:99], v[144:145], v[48:49] op_sel_hi:[1,0]
	v_pk_mul_f32 v[100:101], v[142:143], v[48:49] op_sel_hi:[1,0]
	v_pk_mul_f32 v[102:103], v[48:49], v[140:141] op_sel_hi:[0,1]
	v_pk_mul_f32 v[104:105], v[48:49], v[138:139] op_sel_hi:[0,1]
	v_pk_mul_f32 v[106:107], v[48:49], v[136:137] op_sel_hi:[0,1]
	v_pk_mul_f32 v[48:49], v[48:49], v[134:135] op_sel_hi:[0,1]
	v_add3_u32 v134, s3, v113, v112
	v_add3_u32 v3, s3, v109, v3
	v_bfe_u32 v109, v95, 16, 1
	v_bfe_u32 v113, v94, 16, 1
	v_bfe_u32 v132, v97, 16, 1
	v_bfe_u32 v133, v96, 16, 1
	v_add3_u32 v96, v96, v133, s46
	v_add3_u32 v97, v97, v132, s46
	v_add3_u32 v94, v94, v113, s46
	v_add3_u32 v95, v95, v109, s46
	v_perm_b32 v95, v95, v94, s47
	v_perm_b32 v94, v97, v96, s47
	v_pk_mul_f32 v[96:97], v[130:131], v[100:101]
	v_pk_mul_f32 v[98:99], v[128:129], v[98:99]
	v_bfe_u32 v109, v97, 16, 1
	v_bfe_u32 v100, v99, 16, 1
	v_bfe_u32 v101, v98, 16, 1
	v_bfe_u32 v113, v96, 16, 1
	v_add3_u32 v96, v96, v113, s46
	v_add3_u32 v109, v97, v109, s46
	v_add3_u32 v97, v98, v101, s46
	v_add3_u32 v98, v99, v100, s46
	v_perm_b32 v97, v98, v97, s47
	v_perm_b32 v96, v109, v96, s47
	ds_write2_b64 v3, v[94:95], v[96:97] offset1:2
	v_pk_mul_f32 v[94:95], v[126:127], v[104:105]
	v_pk_mul_f32 v[96:97], v[124:125], v[102:103]
	v_bfe_u32 v100, v95, 16, 1
	v_bfe_u32 v98, v97, 16, 1
	v_bfe_u32 v99, v96, 16, 1
	v_bfe_u32 v101, v94, 16, 1
	v_add3_u32 v100, v95, v100, s46
	v_add3_u32 v95, v96, v99, s46
	v_add3_u32 v96, v97, v98, s46
	v_add3_u32 v94, v94, v101, s46
	v_perm_b32 v95, v96, v95, s47
	v_pk_mul_f32 v[48:49], v[122:123], v[48:49]
	v_pk_mul_f32 v[96:97], v[120:121], v[106:107]
	v_perm_b32 v94, v100, v94, s47
	v_bfe_u32 v98, v97, 16, 1
	v_bfe_u32 v99, v96, 16, 1
	v_bfe_u32 v100, v49, 16, 1
	v_bfe_u32 v101, v48, 16, 1
	v_add3_u32 v48, v48, v101, s46
	v_add3_u32 v100, v49, v100, s46
	v_add3_u32 v49, v96, v99, s46
	v_add3_u32 v96, v97, v98, s46
	v_perm_b32 v49, v96, v49, s47
	v_perm_b32 v48, v100, v48, s47
	ds_write2_b64 v3, v[94:95], v[48:49] offset0:4 offset1:6
	v_pk_mul_f32 v[48:49], v[118:119], v[80:81]
	v_pk_mul_f32 v[78:79], v[116:117], v[78:79]
	v_bfe_u32 v94, v49, 16, 1
	v_bfe_u32 v80, v79, 16, 1
	v_bfe_u32 v81, v78, 16, 1
	v_add3_u32 v94, v49, v94, s46
	v_add3_u32 v49, v78, v81, s46
	v_add3_u32 v78, v79, v80, s46
	v_perm_b32 v49, v78, v49, s47
	v_pk_mul_f32 v[78:79], v[114:115], v[84:85]
	v_pk_mul_f32 v[80:81], v[110:111], v[82:83]
	v_bfe_u32 v95, v48, 16, 1
	v_bfe_u32 v82, v81, 16, 1
	v_bfe_u32 v83, v80, 16, 1
	v_bfe_u32 v84, v79, 16, 1
	v_bfe_u32 v85, v78, 16, 1
	v_add3_u32 v48, v48, v95, s46
	v_add3_u32 v78, v78, v85, s46
	v_add3_u32 v84, v79, v84, s46
	v_add3_u32 v79, v80, v83, s46
	v_add3_u32 v80, v81, v82, s46
	v_perm_b32 v48, v94, v48, s47
	v_perm_b32 v79, v80, v79, s47
	v_perm_b32 v78, v84, v78, s47
	ds_write2_b64 v3, v[48:49], v[78:79] offset0:8 offset1:10
	v_pk_mul_f32 v[48:49], v[68:69], v[88:89]
	v_pk_mul_f32 v[66:67], v[66:67], v[86:87]
	v_bfe_u32 v78, v49, 16, 1
	v_bfe_u32 v68, v67, 16, 1
	v_bfe_u32 v69, v66, 16, 1
	v_add3_u32 v78, v49, v78, s46
	v_add3_u32 v49, v66, v69, s46
	v_add3_u32 v66, v67, v68, s46
	v_pk_mul_f32 v[60:61], v[60:61], v[92:93]
	v_pk_mul_f32 v[58:59], v[58:59], v[90:91]
	v_bfe_u32 v79, v48, 16, 1
	v_perm_b32 v49, v66, v49, s47
	v_bfe_u32 v66, v59, 16, 1
	v_bfe_u32 v67, v58, 16, 1
	v_bfe_u32 v68, v61, 16, 1
	v_bfe_u32 v69, v60, 16, 1
	v_add3_u32 v48, v48, v79, s46
	v_add3_u32 v60, v60, v69, s46
	v_add3_u32 v61, v61, v68, s46
	v_add3_u32 v58, v58, v67, s46
	v_add3_u32 v59, v59, v66, s46
	v_perm_b32 v48, v78, v48, s47
	v_perm_b32 v59, v59, v58, s47
	v_perm_b32 v58, v61, v60, s47
	ds_write2_b64 v3, v[48:49], v[58:59] offset0:12 offset1:14
	s_waitcnt lgkmcnt(0)
	ds_read_b128 v[58:61], v134
	v_mov_b32_e32 v109, v2
	v_lshl_add_u64 v[48:49], s[42:43], 0, v[108:109]
	v_mov_b32_e32 v113, v2
	v_lshl_add_u64 v[48:49], v[48:49], 0, v[112:113]
	s_waitcnt lgkmcnt(0)
	flat_store_dwordx4 v[48:49], v[58:61]
	ds_read_b128 v[58:61], v134 offset:1024
	v_add_co_u32_e32 v66, vcc, s0, v48
	s_mov_b32 s0, 0x10000
	s_nop 0
	v_addc_co_u32_e32 v67, vcc, 0, v49, vcc
	s_waitcnt lgkmcnt(0)
	flat_store_dwordx4 v[66:67], v[58:61]
	ds_read_b128 v[58:61], v134 offset:2048
	v_add_co_u32_e32 v68, vcc, s0, v48
	s_mov_b32 s0, 0x18000
	s_nop 0
	v_addc_co_u32_e32 v69, vcc, 0, v49, vcc
	s_waitcnt lgkmcnt(0)
	flat_store_dwordx4 v[68:69], v[58:61]
	ds_read_b128 v[58:61], v134 offset:3072
	v_add_co_u32_e32 v78, vcc, s0, v48
	v_pk_mul_f32 v[56:57], v[56:57], v[64:65]
	s_nop 0
	v_addc_co_u32_e32 v79, vcc, 0, v49, vcc
	v_pk_mul_f32 v[54:55], v[54:55], v[62:63]
	s_waitcnt lgkmcnt(0)
	flat_store_dwordx4 v[78:79], v[58:61]
	v_pk_mul_f32 v[52:53], v[52:53], v[72:73]
	v_pk_mul_f32 v[50:51], v[50:51], v[70:71]
	v_bfe_u32 v58, v55, 16, 1
	v_bfe_u32 v59, v54, 16, 1
	v_bfe_u32 v60, v57, 16, 1
	v_bfe_u32 v61, v56, 16, 1
	v_add3_u32 v56, v56, v61, s46
	v_add3_u32 v57, v57, v60, s46
	v_add3_u32 v54, v54, v59, s46
	v_add3_u32 v55, v55, v58, s46
	v_perm_b32 v55, v55, v54, s47
	v_perm_b32 v54, v57, v56, s47
	v_bfe_u32 v56, v51, 16, 1
	v_bfe_u32 v57, v50, 16, 1
	v_bfe_u32 v58, v53, 16, 1
	v_bfe_u32 v59, v52, 16, 1
	v_add3_u32 v52, v52, v59, s46
	v_add3_u32 v53, v53, v58, s46
	v_add3_u32 v50, v50, v57, s46
	v_add3_u32 v51, v51, v56, s46
	v_perm_b32 v51, v51, v50, s47
	v_perm_b32 v50, v53, v52, s47
	v_pk_mul_f32 v[40:41], v[40:41], v[76:77]
	v_pk_mul_f32 v[38:39], v[38:39], v[74:75]
	s_waitcnt lgkmcnt(0)
	ds_write2_b64 v3, v[54:55], v[50:51] offset1:2
	v_bfe_u32 v50, v39, 16, 1
	v_bfe_u32 v51, v38, 16, 1
	v_bfe_u32 v52, v41, 16, 1
	v_bfe_u32 v53, v40, 16, 1
	v_add3_u32 v40, v40, v53, s46
	v_add3_u32 v41, v41, v52, s46
	v_add3_u32 v38, v38, v51, s46
	v_add3_u32 v39, v39, v50, s46
	v_pk_mul_f32 v[36:37], v[36:37], v[46:47]
	v_pk_mul_f32 v[34:35], v[34:35], v[44:45]
	v_perm_b32 v39, v39, v38, s47
	v_perm_b32 v38, v41, v40, s47
	v_bfe_u32 v40, v35, 16, 1
	v_bfe_u32 v41, v34, 16, 1
	v_bfe_u32 v44, v37, 16, 1
	v_bfe_u32 v45, v36, 16, 1
	v_add3_u32 v36, v36, v45, s46
	v_add3_u32 v37, v37, v44, s46
	v_add3_u32 v34, v34, v41, s46
	v_add3_u32 v35, v35, v40, s46
	v_perm_b32 v35, v35, v34, s47
	v_perm_b32 v34, v37, v36, s47
	v_pk_mul_f32 v[18:19], v[18:19], v[42:43]
	v_pk_mul_f32 v[16:17], v[16:17], v[32:33]
	ds_write2_b64 v3, v[38:39], v[34:35] offset0:4 offset1:6
	v_bfe_u32 v32, v17, 16, 1
	v_bfe_u32 v33, v16, 16, 1
	v_bfe_u32 v34, v19, 16, 1
	v_bfe_u32 v35, v18, 16, 1
	v_add3_u32 v18, v18, v35, s46
	v_add3_u32 v19, v19, v34, s46
	v_add3_u32 v16, v16, v33, s46
	v_add3_u32 v17, v17, v32, s46
	v_pk_mul_f32 v[14:15], v[14:15], v[30:31]
	v_pk_mul_f32 v[12:13], v[12:13], v[28:29]
	v_perm_b32 v17, v17, v16, s47
	v_perm_b32 v16, v19, v18, s47
	v_bfe_u32 v18, v13, 16, 1
	v_bfe_u32 v19, v12, 16, 1
	v_bfe_u32 v28, v15, 16, 1
	v_bfe_u32 v29, v14, 16, 1
	v_add3_u32 v14, v14, v29, s46
	v_add3_u32 v15, v15, v28, s46
	v_add3_u32 v12, v12, v19, s46
	v_add3_u32 v13, v13, v18, s46
	v_perm_b32 v13, v13, v12, s47
	v_perm_b32 v12, v15, v14, s47
	v_pk_mul_f32 v[10:11], v[10:11], v[26:27]
	v_pk_mul_f32 v[8:9], v[8:9], v[24:25]
	ds_write2_b64 v3, v[16:17], v[12:13] offset0:8 offset1:10
	v_bfe_u32 v12, v9, 16, 1
	v_bfe_u32 v13, v8, 16, 1
	v_bfe_u32 v14, v11, 16, 1
	v_bfe_u32 v15, v10, 16, 1
	v_add3_u32 v10, v10, v15, s46
	v_add3_u32 v11, v11, v14, s46
	v_add3_u32 v8, v8, v13, s46
	v_add3_u32 v9, v9, v12, s46
	v_pk_mul_f32 v[6:7], v[6:7], v[22:23]
	v_pk_mul_f32 v[4:5], v[4:5], v[20:21]
	v_perm_b32 v9, v9, v8, s47
	v_perm_b32 v8, v11, v10, s47
	v_bfe_u32 v10, v5, 16, 1
	v_bfe_u32 v11, v4, 16, 1
	v_bfe_u32 v12, v7, 16, 1
	v_bfe_u32 v13, v6, 16, 1
	v_add3_u32 v6, v6, v13, s46
	v_add3_u32 v7, v7, v12, s46
	v_add3_u32 v4, v4, v11, s46
	v_add3_u32 v5, v5, v10, s46
	v_perm_b32 v5, v5, v4, s47
	v_perm_b32 v4, v7, v6, s47
	ds_write2_b64 v3, v[8:9], v[4:5] offset0:12 offset1:14
	s_waitcnt lgkmcnt(0)
	ds_read_b128 v[4:7], v134
	s_waitcnt lgkmcnt(0)
	flat_store_dwordx4 v[48:49], v[4:7] offset:128
	ds_read_b128 v[4:7], v134 offset:1024
	s_waitcnt lgkmcnt(0)
	flat_store_dwordx4 v[66:67], v[4:7] offset:128
	ds_read_b128 v[4:7], v134 offset:2048
	s_waitcnt lgkmcnt(0)
	flat_store_dwordx4 v[68:69], v[4:7] offset:128
	ds_read_b128 v[4:7], v134 offset:3072
	s_waitcnt lgkmcnt(0)
	flat_store_dwordx4 v[78:79], v[4:7] offset:128
	s_waitcnt lgkmcnt(0)
	s_branch .LBB0_911
